# attention fast loop (large units): reference-max subtraction folded into the QK MFMA SrcC (persistent -m_ref block), 17 fewer VALU per half tile; hazard-clean (2 wait states before the first PV MFMA)
# speedup vs baseline: 1.0087x; 1.0087x over previous
; __device__ __forceinline__ int swz(int row) { return ((row & 3) << 2) | ((row >> 2) & 3); }
; __device__ __forceinline__ void dma_tile(const bf16* kbase, const bf16* vbase, int key0, ldsp stage, int wave, int lane) {
;     ...
;     for (int j = 0; j < 2; ++j) { const int rowb = 8 * wave + 4 * j, row = rowb + (lane >> 4), cc = (lane & 15) ^ swz(row); const size_t off = (size_t)(key0 + row) * 128 + cc * 8;
;         glds16(kbase + off, sb + rowb * 256);
;         glds16(vbase + off, sb + RKV + rowb * 256); }
; __device__ __forceinline__ void diff_unit(const bf16* proj, bf16* og0, const float* nwv, float lam_full, float one_m_li, int h, int qb, ldsp lds, int tid, int lane, int wave, int mode) {
;     ...
;     for (int i = 2; i < nt; ++i) {
;         asm volatile("s_waitcnt vmcnt(8)" ::: "memory");
;         __builtin_amdgcn_s_barrier();
;         asm volatile("" ::: "memory");
;         { int n = i + 3; n = n < nt ? n : nt - 1; dma_tile(kbase, vbase, 64 * (n - 2), lds + ((i + 3) & 3) * RSTG, wave, lane); }
;         ldsp Ks = lds + (i & 3) * RSTG, Vs = Ks + RKV;
;         flash_fast_tile2<4>(Ks, Vs, M, qf, o, mc, l);
.LBB0_433:
	s_mov_b32 s6, 2
	s_add_i32 s7, s9, 2
	s_or_b32 s8, s9, 1
	s_cmp_lt_u32 5, s7
	s_cselect_b32 s1, 5, s8
	v_lshl_add_u32 v230, s1, 6, v183
	v_add_u32_e32 v231, s35, v230
	v_add_u32_e32 v230, s31, v230
	v_lshlrev_b32_e32 v231, 8, v231
	v_lshlrev_b32_e32 v230, 8, v230
	v_lshl_add_u32 v231, v156, 1, v231
	v_lshl_add_u32 v230, v154, 1, v230
	s_and_b64 vcc, exec, s[20:21]
	s_cbranch_vccnz .Lap_skip1
	s_setprio 1
.Lap_skip1:
	v_sub_f32_e32 v214, 0, v206
	v_sub_f32_e32 v215, 0, v206
	v_sub_f32_e32 v216, 0, v206
	v_sub_f32_e32 v217, 0, v206
	v_sub_f32_e32 v218, 0, v206
	v_sub_f32_e32 v219, 0, v206
	v_sub_f32_e32 v220, 0, v206
	v_sub_f32_e32 v221, 0, v206
	v_sub_f32_e32 v222, 0, v206
	v_sub_f32_e32 v223, 0, v206
	v_sub_f32_e32 v224, 0, v206
	v_sub_f32_e32 v225, 0, v206
	v_sub_f32_e32 v226, 0, v206
	v_sub_f32_e32 v227, 0, v206
	v_sub_f32_e32 v228, 0, v206
	v_sub_f32_e32 v229, 0, v206
	s_branch .LBB0_435

; #define LAS __attribute__((address_space(3)))
; template <int KS>
; __device__ __forceinline__ void flash_fast_tile2(ldsp Ks, ldsp Vs, const FragMap<KS>& M, const bf16x8 (&qf)[KS], f32x16 (&o)[4], float& mc, float& l) {
;     bf16x8 kf[KS];
; #pragma unroll
;     for (int ks = 0; ks < KS; ++ks) kf[ks] = *(LAS const bf16x8*)(Ks + M.k[ks]);
; #pragma unroll 1
;     for (int h = 0; h < 2; ++h) {
;         ldsp Vh = Vs + h * 32 * 256;
;         s16x4 vl[8], vh[8];
; #pragma unroll
;         for (int b = 0; b < 4; ++b) { vl[2 * b] = vtr(Vh + M.v[0][b]); vh[2 * b] = vtr(Vh + M.v[1][b]); vl[2 * b + 1] = vtr(Vh + 16 * 256 + M.v[0][b]); vh[2 * b + 1] = vtr(Vh + 16 * 256 + M.v[1][b]); }
;         f32x16 s0;
; #pragma unroll
;         for (int r = 0; r < 16; ++r) s0[r] = 0.f;
; #pragma unroll
;         for (int ks = 0; ks < KS; ++ks) s0 = MFMA32(kf[ks], qf[ks], s0);
;         if (h == 0) {
; #pragma unroll
;             for (int ks = 0; ks < KS; ++ks) kf[ks] = *(LAS const bf16x8*)(Ks + 32 * 256 + M.k[ks]); }
;         float m0 = fmaxf(s0[0], s0[1]), m1 = fmaxf(s0[2], s0[3]);
; #pragma unroll
;         for (int r = 4; r < 16; r += 4) { m0 = fmaxf(fmaxf(m0, s0[r]), s0[r + 1]); m1 = fmaxf(fmaxf(m1, s0[r + 2]), s0[r + 3]); }
;         const float mx = xmax32(fmaxf(m0, m1));
;         if (!__all(mx - mc <= 6.f)) {
;             const float mnew = fmaxf(mc, mx), alpha = __builtin_amdgcn_exp2f(mc - mnew);
;             mc = mnew; l *= alpha;
; #pragma unroll
;             for (int b = 0; b < 4; ++b) o[b] *= alpha;
;         }
;         float ps0 = 0.f, ps1 = 0.f;
; #pragma unroll
;         for (int r = 0; r < 16; r += 2) { s0[r] = __builtin_amdgcn_exp2f(s0[r] - mc); s0[r + 1] = __builtin_amdgcn_exp2f(s0[r + 1] - mc); ps0 += s0[r]; ps1 += s0[r + 1]; }
;         l += ps0 + ps1;
;         const bf16x8 p0 = pack8<0>(s0), p1 = pack8<1>(s0);
; #pragma unroll
;         for (int b = 0; b < 4; ++b) {
;             o[b] = MFMA32(cat8(vl[2 * b], vh[2 * b]), p0, o[b]);
;             o[b] = MFMA32(cat8(vl[2 * b + 1], vh[2 * b + 1]), p1, o[b]); }
; __device__ __forceinline__ void diff_unit(const bf16* proj, bf16* og0, const float* nwv, float lam_full, float one_m_li, int h, int qb, ldsp lds, int tid, int lane, int wave, int mode) {
;     ...
;         { int n = i + 3; n = n < nt ? n : nt - 1; dma_tile(kbase, vbase, 64 * (n - 2), lds + ((i + 3) & 3) * RSTG, wave, lane); }
.LBB0_435:
	s_add_i32 s0, s6, 3
	s_lshl_b32 s0, s0, 15
	s_and_b32 s0, s0, 0x18000
	s_waitcnt vmcnt(8)
	s_barrier
	s_add_i32 s1, s0, 0x4000
	s_add_i32 m0, s34, s0
	s_add_i32 s4, s6, 4
	global_load_lds_dwordx4 v230, s[24:25]
	s_add_i32 m0, s1, s34
	s_nop 0
	global_load_lds_dwordx4 v230, s[26:27]
	s_add_i32 m0, s36, s0
	s_nop 0
	global_load_lds_dwordx4 v231, s[24:25]
	s_add_i32 m0, s1, s36
	s_cmp_lt_u32 s4, s7
	global_load_lds_dwordx4 v231, s[26:27]
	s_cselect_b32 s4, 0x4000, 0
	v_add_u32_e32 v230, s4, v230
	v_add_u32_e32 v231, s4, v231
	s_lshl_b32 s0, s6, 15
	s_and_b32 s0, s0, 0x18000
	s_add_i32 s9, s0, 0
	v_add_u32_e32 v207, s9, v165
	v_add_u32_e32 v209, s9, v169
	v_add_u32_e32 v208, s9, v167
	ds_read_b128 v[98:101], v207
	ds_read_b128 v[102:105], v208
	v_add_u32_e32 v210, s9, v171
	ds_read_b128 v[106:109], v209
	ds_read_b128 v[110:113], v210
	s_mov_b32 s10, 0
	s_mov_b64 s[0:1], -1
	s_branch .LBB0_437
.LBB0_436:
	v_exp_f32_e32 v66, v66
	v_exp_f32_e32 v67, v67
	v_exp_f32_e32 v68, v68
	v_exp_f32_e32 v69, v69
	v_exp_f32_e32 v70, v70
	v_exp_f32_e32 v71, v71
	v_exp_f32_e32 v72, v72
	v_exp_f32_e32 v73, v73
	v_add_f32_e32 v212, v66, v68
	v_add_f32_e32 v213, v67, v69
	v_cvt_pk_bf16_f32 v66, v66, v67
	v_cvt_pk_bf16_f32 v67, v68, v69
	v_cvt_pk_bf16_f32 v68, v70, v71
	v_cvt_pk_bf16_f32 v69, v72, v73
	v_exp_f32_e32 v74, v74
	v_exp_f32_e32 v75, v75
	v_mfma_f32_32x32x16_bf16 v[50:65], v[142:145], v[66:69], v[50:65]
	s_waitcnt lgkmcnt(10)
	v_mfma_f32_32x32x16_bf16 v[34:49], v[134:137], v[66:69], v[34:49]
	v_exp_f32_e32 v76, v76
	v_exp_f32_e32 v77, v77
	v_exp_f32_e32 v78, v78
	v_exp_f32_e32 v79, v79
	v_exp_f32_e32 v80, v80
	v_exp_f32_e32 v81, v81
	s_waitcnt lgkmcnt(6)
	v_mfma_f32_32x32x16_bf16 v[18:33], v[126:129], v[66:69], v[18:33]
	v_add_f32_e64 v212, v70, v212
	v_add_f32_e64 v213, v71, v213
	v_cvt_pk_bf16_f32 v70, v74, v75
	v_add_f32_e64 v212, v72, v212
	v_add_f32_e64 v213, v73, v213
	v_cvt_pk_bf16_f32 v71, v76, v77
	v_cvt_pk_bf16_f32 v72, v78, v79
	v_cvt_pk_bf16_f32 v73, v80, v81
	v_add_f32_e32 v212, v74, v212
	v_add_f32_e32 v213, v75, v213
	s_waitcnt lgkmcnt(2)
	v_mfma_f32_32x32x16_bf16 v[2:17], v[114:117], v[66:69], v[2:17]
	v_add_f32_e64 v212, v76, v212
	v_add_f32_e64 v213, v77, v213
	s_movk_i32 s10, 0x2000
	v_add_f32_e64 v212, v78, v212
	v_add_f32_e64 v213, v79, v213
	s_mov_b64 s[0:1], 0
	v_add_f32_e32 v212, v80, v212
	v_add_f32_e32 v213, v81, v213
	s_andn2_b64 vcc, exec, s[4:5]
	v_add_f32_e32 v211, v212, v213
	v_mfma_f32_32x32x16_bf16 v[50:65], v[138:141], v[70:73], v[50:65]
	v_add_f32_e32 v195, v195, v211
	v_mfma_f32_32x32x16_bf16 v[34:49], v[130:133], v[70:73], v[34:49]
	v_mfma_f32_32x32x16_bf16 v[18:33], v[122:125], v[70:73], v[18:33]
	s_waitcnt lgkmcnt(0)
	v_mfma_f32_32x32x16_bf16 v[2:17], v[118:121], v[70:73], v[2:17]
	s_cbranch_vccz .LBB0_434
.LBB0_437:
	s_xor_b64 s[4:5], s[0:1], -1
	s_add_i32 s0, s9, s10
	v_add_u32_e32 v66, s0, v173
	v_add_u32_e32 v67, s0, v189
	ds_read_b64_tr_b16 v[142:143], v66 offset:16384
	ds_read_b64_tr_b16 v[144:145], v67 offset:18432
	ds_read_b64_tr_b16 v[138:139], v66 offset:20480
	ds_read_b64_tr_b16 v[140:141], v67 offset:22528
	v_add_u32_e32 v66, s0, v175
	v_add_u32_e32 v67, s0, v248
	ds_read_b64_tr_b16 v[134:135], v66 offset:16384
	ds_read_b64_tr_b16 v[136:137], v67 offset:18432
	ds_read_b64_tr_b16 v[130:131], v66 offset:20480
	ds_read_b64_tr_b16 v[132:133], v67 offset:22528
	v_add_u32_e32 v66, s0, v177
	v_add_u32_e32 v67, s0, v249
	ds_read_b64_tr_b16 v[126:127], v66 offset:16384
	ds_read_b64_tr_b16 v[128:129], v67 offset:18432
	ds_read_b64_tr_b16 v[122:123], v66 offset:20480
	ds_read_b64_tr_b16 v[124:125], v67 offset:22528
	v_add_u32_e32 v66, s0, v179
	v_add_u32_e32 v67, s0, v250
	ds_read_b64_tr_b16 v[114:115], v66 offset:16384
	ds_read_b64_tr_b16 v[116:117], v67 offset:18432
	ds_read_b64_tr_b16 v[118:119], v66 offset:20480
	ds_read_b64_tr_b16 v[120:121], v67 offset:22528
	s_waitcnt lgkmcnt(14)
	v_mfma_f32_32x32x16_bf16 v[66:81], v[98:101], v[82:85], v[214:229]
	s_and_b64 vcc, exec, s[4:5]
	v_mfma_f32_32x32x16_bf16 v[66:81], v[102:105], v[86:89], v[66:81]
	v_mfma_f32_32x32x16_bf16 v[66:81], v[106:109], v[90:93], v[66:81]
	v_mfma_f32_32x32x16_bf16 v[66:81], v[110:113], v[94:97], v[66:81]
	s_cbranch_vccnz .LBB0_439
	ds_read_b128 v[98:101], v207 offset:8192
	ds_read_b128 v[102:105], v208 offset:8192
	ds_read_b128 v[106:109], v209 offset:8192
	ds_read_b128 v[110:113], v210 offset:8192
; __device__ __forceinline__ float xmax32(float v) { auto rr = __builtin_amdgcn_permlane32_swap(__float_as_uint(v), __float_as_uint(v), false, false); return fmaxf(__uint_as_float(rr[0]), __uint_as_float(rr[1])); }
; template <int KS>
; __device__ __forceinline__ void flash_fast_tile2(ldsp Ks, ldsp Vs, const FragMap<KS>& M, const bf16x8 (&qf)[KS], f32x16 (&o)[4], float& mc, float& l) {
;     ...
;         float m0 = fmaxf(s0[0], s0[1]), m1 = fmaxf(s0[2], s0[3]);
; #pragma unroll
;         for (int r = 4; r < 16; r += 4) { m0 = fmaxf(fmaxf(m0, s0[r]), s0[r + 1]); m1 = fmaxf(fmaxf(m1, s0[r + 2]), s0[r + 3]); }
;         const float mx = xmax32(fmaxf(m0, m1));
;         if (!__all(mx - mc <= 6.f)) {
;             const float mnew = fmaxf(mc, mx), alpha = __builtin_amdgcn_exp2f(mc - mnew);
;             mc = mnew; l *= alpha;
; #pragma unroll
;             for (int b = 0; b < 4; ++b) o[b] *= alpha;
;         }
.LBB0_439:
	s_nop 10
	v_max_f32_e32 v211, v68, v69
	v_max3_f32 v212, v66, v67, v70
	v_max3_f32 v211, v211, v72, v73
	v_max3_f32 v212, v212, v71, v74
	v_max3_f32 v211, v211, v76, v77
	v_max3_f32 v212, v212, v75, v78
	v_max3_f32 v211, v211, v80, v81
	v_max3_f32 v211, v212, v79, v211
	v_mov_b32_e32 v212, v211
	s_nop 1
	v_permlane32_swap_b32_e32 v211, v212
	v_max_f32_e32 v211, v211, v212
	v_cmp_ge_f32_e32 vcc, s53, v211
	s_cmp_eq_u64 vcc, exec
	s_cbranch_scc1 .LBB0_436
	v_max_f32_e32 v213, 0, v211
	v_sub_f32_e32 v212, 0, v213
	v_exp_f32_e32 v212, v212
	v_add_f32_e32 v206, v206, v213
	v_sub_f32_e32 v66, v66, v213
	v_sub_f32_e32 v67, v67, v213
	v_sub_f32_e32 v68, v68, v213
	v_sub_f32_e32 v69, v69, v213
	v_sub_f32_e32 v70, v70, v213
	v_sub_f32_e32 v71, v71, v213
	v_sub_f32_e32 v72, v72, v213
	v_sub_f32_e32 v73, v73, v213
	v_sub_f32_e32 v74, v74, v213
	v_sub_f32_e32 v75, v75, v213
	v_sub_f32_e32 v76, v76, v213
	v_sub_f32_e32 v77, v77, v213
	v_sub_f32_e32 v78, v78, v213
	v_sub_f32_e32 v79, v79, v213
	v_sub_f32_e32 v80, v80, v213
	v_sub_f32_e32 v81, v81, v213
	v_sub_f32_e32 v214, v214, v213
	v_sub_f32_e32 v215, v215, v213
	v_sub_f32_e32 v216, v216, v213
	v_sub_f32_e32 v217, v217, v213
	v_sub_f32_e32 v218, v218, v213
	v_sub_f32_e32 v219, v219, v213
	v_sub_f32_e32 v220, v220, v213
	v_sub_f32_e32 v221, v221, v213
	v_sub_f32_e32 v222, v222, v213
	v_sub_f32_e32 v223, v223, v213
	v_sub_f32_e32 v224, v224, v213
	v_sub_f32_e32 v225, v225, v213
	v_sub_f32_e32 v226, v226, v213
	v_sub_f32_e32 v227, v227, v213
	v_sub_f32_e32 v228, v228, v213
	v_sub_f32_e32 v229, v229, v213
	v_mul_f32_e32 v195, v195, v212
	v_pk_mul_f32 v[64:65], v[64:65], v[212:213] op_sel_hi:[1,0]
	v_pk_mul_f32 v[62:63], v[62:63], v[212:213] op_sel_hi:[1,0]
	v_pk_mul_f32 v[60:61], v[60:61], v[212:213] op_sel_hi:[1,0]
	v_pk_mul_f32 v[58:59], v[58:59], v[212:213] op_sel_hi:[1,0]
	v_pk_mul_f32 v[56:57], v[56:57], v[212:213] op_sel_hi:[1,0]
	v_pk_mul_f32 v[54:55], v[54:55], v[212:213] op_sel_hi:[1,0]
	v_pk_mul_f32 v[52:53], v[52:53], v[212:213] op_sel_hi:[1,0]
	v_pk_mul_f32 v[50:51], v[50:51], v[212:213] op_sel_hi:[1,0]
	v_pk_mul_f32 v[48:49], v[48:49], v[212:213] op_sel_hi:[1,0]
	v_pk_mul_f32 v[46:47], v[46:47], v[212:213] op_sel_hi:[1,0]
	v_pk_mul_f32 v[44:45], v[44:45], v[212:213] op_sel_hi:[1,0]
	v_pk_mul_f32 v[42:43], v[42:43], v[212:213] op_sel_hi:[1,0]
	v_pk_mul_f32 v[40:41], v[40:41], v[212:213] op_sel_hi:[1,0]
	v_pk_mul_f32 v[38:39], v[38:39], v[212:213] op_sel_hi:[1,0]
	v_pk_mul_f32 v[36:37], v[36:37], v[212:213] op_sel_hi:[1,0]
	v_pk_mul_f32 v[34:35], v[34:35], v[212:213] op_sel_hi:[1,0]
	v_pk_mul_f32 v[32:33], v[32:33], v[212:213] op_sel_hi:[1,0]
	v_pk_mul_f32 v[30:31], v[30:31], v[212:213] op_sel_hi:[1,0]
	v_pk_mul_f32 v[28:29], v[28:29], v[212:213] op_sel_hi:[1,0]
	v_pk_mul_f32 v[26:27], v[26:27], v[212:213] op_sel_hi:[1,0]
	v_pk_mul_f32 v[24:25], v[24:25], v[212:213] op_sel_hi:[1,0]
	v_pk_mul_f32 v[22:23], v[22:23], v[212:213] op_sel_hi:[1,0]
	v_pk_mul_f32 v[20:21], v[20:21], v[212:213] op_sel_hi:[1,0]
	v_pk_mul_f32 v[18:19], v[18:19], v[212:213] op_sel_hi:[1,0]
	v_pk_mul_f32 v[16:17], v[16:17], v[212:213] op_sel_hi:[1,0]
	v_pk_mul_f32 v[14:15], v[14:15], v[212:213] op_sel_hi:[1,0]
	v_pk_mul_f32 v[12:13], v[12:13], v[212:213] op_sel_hi:[1,0]
	v_pk_mul_f32 v[10:11], v[10:11], v[212:213] op_sel_hi:[1,0]
	v_pk_mul_f32 v[8:9], v[8:9], v[212:213] op_sel_hi:[1,0]
	v_pk_mul_f32 v[6:7], v[6:7], v[212:213] op_sel_hi:[1,0]
	v_pk_mul_f32 v[4:5], v[4:5], v[212:213] op_sel_hi:[1,0]
	v_pk_mul_f32 v[2:3], v[2:3], v[212:213] op_sel_hi:[1,0]
	s_branch .LBB0_436
